# speedup vs baseline: 1.0041x; 1.0006x over previous
; DEV void gemm_tile(const u16* __restrict__ A, const u16* __restrict__ Bt, u16* __restrict__ C, int N, int K,
;                    int brow, int bcol, unsigned char* smem, int epi, const GateEpi& ge) {
;     ...
;   u16* Cw = C + (size_t)(brow + wr * 64) * N + bcol + wc * 32;
; #pragma unroll
;   for (int ai = 0; ai < 2; ++ai)
; #pragma unroll
;     for (int bj = 0; bj < 2; ++bj)
; #pragma unroll
;       for (int m = 0; m < 4; ++m)
; #pragma unroll
;         for (int n = 0; n < 2; ++n)
; #pragma unroll
;           for (int j = 0; j < 4; ++j)
;             Cw[(size_t)(ai * 128 + m * 16 + fq2 * 4 + j) * N + (bj * 128 + n * 16 + fr2)] = f2bf(acc[ai][bj][m][n][j]);
.Lg_epi:
	v_readfirstlane_b32 s0, v160
	s_andn2_b32 s0, s0, 63
	s_andn2_b64 vcc, exec, s[2:3]
	v_or_b32_e32 v180, s0, v161
	s_nop 0
	v_bfe_u32 v181, v180, 4, 2
	v_and_b32_e32 v180, 15, v180
	s_cbranch_vccz .Lg_gate
	s_add_i32 s0, s51, s49
	s_mul_hi_u32 s1, s0, s44
	s_mul_i32 s0, s0, s44
	s_lshl_b64 s[0:1], s[0:1], 1
	s_add_u32 s0, s14, s0
	s_addc_u32 s1, s15, s1
	s_lshl_b64 s[4:5], s[92:93], 1
	s_add_u32 s0, s0, s4
	s_addc_u32 s1, s1, s5
	s_lshl_b32 s4, s50, 6
	s_add_u32 s0, s0, s4
	s_addc_u32 s1, s1, 0
	v_mul_u32_u24_e32 v153, s44, v180
	v_lshlrev_b32_e32 v153, 1, v153
	v_lshl_add_u32 v153, v181, 4, v153
	s_lshl_b32 s4, s44, 5
	s_lshl_b32 s5, s44, 7
	v_cvt_pk_bf16_f32 v184, v124, v125
	v_cvt_pk_bf16_f32 v185, v126, v127
	v_cvt_pk_bf16_f32 v186, v120, v121
	v_cvt_pk_bf16_f32 v187, v122, v123
	global_store_dwordx4 v153, v[184:187], s[0:1]
	s_mov_b64 exec, 0xffffffff
	global_store_dwordx4 v153, v[184:187], s[0:1]
	s_mov_b64 exec, -1
	v_cvt_pk_bf16_f32 v188, v84, v85
	v_cvt_pk_bf16_f32 v189, v86, v87
	v_cvt_pk_bf16_f32 v190, v68, v69
	v_cvt_pk_bf16_f32 v191, v70, v71
	global_store_dwordx4 v153, v[188:191], s[0:1] offset:256
	s_mov_b64 exec, 0xffffffff
	global_store_dwordx4 v153, v[188:191], s[0:1] offset:256
	s_mov_b64 exec, -1
	s_add_u32 s0, s0, s4
	s_addc_u32 s1, s1, 0
	v_cvt_pk_bf16_f32 v192, v116, v117
	v_cvt_pk_bf16_f32 v193, v118, v119
	v_cvt_pk_bf16_f32 v194, v112, v113
	v_cvt_pk_bf16_f32 v195, v114, v115
	global_store_dwordx4 v153, v[192:195], s[0:1]
	s_mov_b64 exec, 0xffffffff
	global_store_dwordx4 v153, v[192:195], s[0:1]
	s_mov_b64 exec, -1
	v_cvt_pk_bf16_f32 v196, v52, v53
	v_cvt_pk_bf16_f32 v197, v54, v55
	v_cvt_pk_bf16_f32 v198, v48, v49
	v_cvt_pk_bf16_f32 v199, v50, v51
	global_store_dwordx4 v153, v[196:199], s[0:1] offset:256
	s_mov_b64 exec, 0xffffffff
	global_store_dwordx4 v153, v[196:199], s[0:1] offset:256
	s_mov_b64 exec, -1
	s_add_u32 s0, s0, s4
	s_addc_u32 s1, s1, 0
	v_cvt_pk_bf16_f32 v184, v108, v109
	v_cvt_pk_bf16_f32 v185, v110, v111
	v_cvt_pk_bf16_f32 v186, v104, v105
	v_cvt_pk_bf16_f32 v187, v106, v107
	global_store_dwordx4 v153, v[184:187], s[0:1]
	s_mov_b64 exec, 0xffffffff
	global_store_dwordx4 v153, v[184:187], s[0:1]
	s_mov_b64 exec, -1
	v_cvt_pk_bf16_f32 v188, v44, v45
	v_cvt_pk_bf16_f32 v189, v46, v47
	v_cvt_pk_bf16_f32 v190, v40, v41
	v_cvt_pk_bf16_f32 v191, v42, v43
	global_store_dwordx4 v153, v[188:191], s[0:1] offset:256
	s_mov_b64 exec, 0xffffffff
	global_store_dwordx4 v153, v[188:191], s[0:1] offset:256
	s_mov_b64 exec, -1
	s_add_u32 s0, s0, s4
	s_addc_u32 s1, s1, 0
	v_cvt_pk_bf16_f32 v192, v100, v101
	v_cvt_pk_bf16_f32 v193, v102, v103
	v_cvt_pk_bf16_f32 v194, v96, v97
	v_cvt_pk_bf16_f32 v195, v98, v99
	global_store_dwordx4 v153, v[192:195], s[0:1]
	s_mov_b64 exec, 0xffffffff
	global_store_dwordx4 v153, v[192:195], s[0:1]
	s_mov_b64 exec, -1
	v_cvt_pk_bf16_f32 v196, v36, v37
	v_cvt_pk_bf16_f32 v197, v38, v39
	v_cvt_pk_bf16_f32 v198, v32, v33
	v_cvt_pk_bf16_f32 v199, v34, v35
	global_store_dwordx4 v153, v[196:199], s[0:1] offset:256
	s_mov_b64 exec, 0xffffffff
	global_store_dwordx4 v153, v[196:199], s[0:1] offset:256
	s_mov_b64 exec, -1
	s_add_u32 s0, s0, s4
	s_addc_u32 s1, s1, 0
	s_add_u32 s0, s0, s5
	s_addc_u32 s1, s1, 0
	v_cvt_pk_bf16_f32 v184, v28, v29
	v_cvt_pk_bf16_f32 v185, v30, v31
	v_cvt_pk_bf16_f32 v186, v24, v25
	v_cvt_pk_bf16_f32 v187, v26, v27
	global_store_dwordx4 v153, v[184:187], s[0:1]
	s_mov_b64 exec, 0xffffffff
	global_store_dwordx4 v153, v[184:187], s[0:1]
	s_mov_b64 exec, -1
	v_cvt_pk_bf16_f32 v188, v56, v57
	v_cvt_pk_bf16_f32 v189, v58, v59
	v_cvt_pk_bf16_f32 v190, v60, v61
	v_cvt_pk_bf16_f32 v191, v62, v63
	global_store_dwordx4 v153, v[188:191], s[0:1] offset:256
	s_mov_b64 exec, 0xffffffff
	global_store_dwordx4 v153, v[188:191], s[0:1] offset:256
	s_mov_b64 exec, -1
	s_add_u32 s0, s0, s4
	s_addc_u32 s1, s1, 0
	v_cvt_pk_bf16_f32 v192, v20, v21
	v_cvt_pk_bf16_f32 v193, v22, v23
	v_cvt_pk_bf16_f32 v194, v16, v17
	v_cvt_pk_bf16_f32 v195, v18, v19
	global_store_dwordx4 v153, v[192:195], s[0:1]
	s_mov_b64 exec, 0xffffffff
	global_store_dwordx4 v153, v[192:195], s[0:1]
	s_mov_b64 exec, -1
	v_cvt_pk_bf16_f32 v196, v64, v65
	v_cvt_pk_bf16_f32 v197, v66, v67
	v_cvt_pk_bf16_f32 v198, v72, v73
	v_cvt_pk_bf16_f32 v199, v74, v75
	global_store_dwordx4 v153, v[196:199], s[0:1] offset:256
	s_mov_b64 exec, 0xffffffff
	global_store_dwordx4 v153, v[196:199], s[0:1] offset:256
	s_mov_b64 exec, -1
	s_add_u32 s0, s0, s4
	s_addc_u32 s1, s1, 0
	v_cvt_pk_bf16_f32 v184, v12, v13
	v_cvt_pk_bf16_f32 v185, v14, v15
	v_cvt_pk_bf16_f32 v186, v8, v9
	v_cvt_pk_bf16_f32 v187, v10, v11
	global_store_dwordx4 v153, v[184:187], s[0:1]
	s_mov_b64 exec, 0xffffffff
	global_store_dwordx4 v153, v[184:187], s[0:1]
	s_mov_b64 exec, -1
	v_cvt_pk_bf16_f32 v188, v76, v77
	v_cvt_pk_bf16_f32 v189, v78, v79
	v_cvt_pk_bf16_f32 v190, v80, v81
	v_cvt_pk_bf16_f32 v191, v82, v83
	global_store_dwordx4 v153, v[188:191], s[0:1] offset:256
	s_mov_b64 exec, 0xffffffff
	global_store_dwordx4 v153, v[188:191], s[0:1] offset:256
	s_mov_b64 exec, -1
	s_add_u32 s0, s0, s4
	s_addc_u32 s1, s1, 0
	v_cvt_pk_bf16_f32 v192, v4, v5
	v_cvt_pk_bf16_f32 v193, v6, v7
	v_cvt_pk_bf16_f32 v194, v0, v1
	v_cvt_pk_bf16_f32 v195, v2, v3
	global_store_dwordx4 v153, v[192:195], s[0:1]
	s_mov_b64 exec, 0xffffffff
	global_store_dwordx4 v153, v[192:195], s[0:1]
	s_mov_b64 exec, -1
	v_cvt_pk_bf16_f32 v196, v88, v89
	v_cvt_pk_bf16_f32 v197, v90, v91
	v_cvt_pk_bf16_f32 v198, v92, v93
	v_cvt_pk_bf16_f32 v199, v94, v95
	global_store_dwordx4 v153, v[196:199], s[0:1] offset:256
	s_mov_b64 exec, 0xffffffff
	global_store_dwordx4 v153, v[196:199], s[0:1] offset:256
	s_mov_b64 exec, -1
	s_branch .Lg_post
